# lever 10 for both GLA types: HGRN2 recurrence also on the f32 matrix cores (log2-decay prefix/suffix DPP scans, chunk of 16 tokens) + LDS layouts padded (K/Q rows 528 B, exchange rows 1040 B, scratch
# speedup vs baseline: 1.0078x; 1.0078x over previous
.LBB0_242:
	s_andn2_b64 vcc, exec, s[8:9]
	s_cbranch_vccnz .LBB0_184
	s_lshr_b32 s20, s1, 2
	s_and_b32 s21, s1, 3
	s_lshr_b32 s14, s20, 4
	s_xor_b32 s14, s14, 1
	s_bfe_u32 s22, s20, 0x20002
	s_and_b32 s23, s20, 3
	s_mul_i32 s24, s14, 6144
	s_lshl_b32 s25, s23, 8
	s_add_u32 s24, s24, s25
	s_addk_i32 s24, 3072
	s_mul_i32 s25, s22, 0x6800000
	s_add_u32 s24, s24, s25
	s_add_u32 s8, s78, 0x15e00000
	s_addc_u32 s9, s79, 0
	s_add_u32 s8, s8, s24
	s_addc_u32 s9, s9, 0
	s_lshl_b32 s24, s14, 11
	s_lshl_b32 s25, s23, 8
	s_add_u32 s24, s24, s25
	s_lshl_b32 s25, s21, 6
	s_add_u32 s24, s24, s25
	s_addk_i32 s24, 1024
	s_lshl_b32 s25, s22, 25
	s_add_u32 s24, s24, s25
	s_add_u32 s10, s78, 0x2fe00000
	s_addc_u32 s11, s79, 0
	s_add_u32 s10, s10, s24
	s_addc_u32 s11, s11, 0
	s_lshl_b32 s24, s14, 23
	s_lshl_b32 s25, s22, 21
	s_add_u32 s24, s24, s25
	s_lshl_b32 s25, s23, 6
	s_add_u32 s24, s24, s25
	s_lshl_b32 s25, s21, 4
	s_add_u32 s24, s24, s25
	s_add_u32 s12, s78, 0x3ae90000
	s_addc_u32 s13, s79, 0
	s_add_u32 s12, s12, s24
	s_addc_u32 s13, s13, 0
	v_lshrrev_b32_e32 v154, 5, v163
	v_and_b32_e32 v155, 31, v163
	v_bfe_u32 v156, v163, 4, 4
	v_and_b32_e32 v157, 15, v163
	v_lshrrev_b32_e32 v160, 6, v163
	v_mul_u32_u24_e32 v130, 0x3400, v154
	v_lshl_add_u32 v130, v155, 3, v130
	v_mul_u32_u24_e32 v131, 0x3400, v156
	v_lshl_add_u32 v131, v157, 2, v131
	s_lshl_b32 s24, s21, 6
	s_addk_i32 s24, 2048
	v_add_u32_e32 v131, s24, v131
	v_readfirstlane_b32 s16, v160
	v_lshlrev_b32_e32 v132, 12, v154
	v_lshl_add_u32 v132, v155, 1, v132
	v_lshlrev_b32_e32 v133, 8, v154
	v_and_b32_e32 v134, 0xfffffff0, v163
	v_lshlrev_b32_e32 v135, 4, v157
	v_mul_u32_u24_e32 v139, 528, v154
	v_lshl_add_u32 v139, v155, 4, v139
	v_and_b32_e32 v158, 7, v157
	v_lshlrev_b32_e32 v158, 5, v158
	v_lshrrev_b32_e32 v159, 3, v157
	v_lshl_add_u32 v158, v159, 2, v158
	v_and_b32_e32 v159, 1, v156
	v_lshl_add_u32 v158, v159, 3, v158
	v_lshrrev_b32_e32 v159, 1, v156
	v_lshl_add_u32 v158, v159, 8, v158
	v_add_u32_e32 v140, 0x6800, v158
	v_add_u32_e32 v153, 0xe800, v158
	v_bfe_u32 v158, v163, 4, 1
	v_bfe_u32 v159, v163, 5, 1
	v_lshlrev_b32_e32 v158, 3, v158
	v_lshl_add_u32 v158, v159, 2, v158
	v_lshl_add_u32 v158, v158, 3, v160
	v_lshlrev_b32_e32 v158, 7, v158
	v_lshl_add_u32 v158, v157, 2, v158
	v_add_u32_e32 v141, 0x10000, v158
	v_add_u32_e32 v142, 0x10400, v158
	v_add_u32_e32 v143, 0x10800, v158
	v_add_u32_e32 v144, 0x10c00, v158
	v_add_u32_e32 v145, 0x14000, v158
	v_add_u32_e32 v146, 0x14400, v158
	v_add_u32_e32 v147, 0x14800, v158
	v_add_u32_e32 v148, 0x14c00, v158
	v_mul_u32_u24_e32 v161, 1040, v154
	v_lshl_add_u32 v161, v155, 2, v161
	v_add_u32_e32 v149, 0x10000, v161
	v_add_u32_e32 v150, 0x14400, v161
	s_sub_u32 s24, 122, s23
	s_lshl_b32 s24, s24, 23
	v_mov_b32_e32 v100, s24
	v_sub_f32_e32 v100, 1.0, v100
	v_mov_b32_e32 v101, v100
	v_mov_b32_e32 v0, 0
	v_mov_b32_e32 v1, 0
	v_mov_b32_e32 v2, 0
	v_mov_b32_e32 v3, 0
	v_mov_b32_e32 v4, 0
	v_mov_b32_e32 v5, 0
	v_mov_b32_e32 v6, 0
	v_mov_b32_e32 v7, 0
	s_mov_b32 s18, 1
	s_mov_b32 s19, 1
	s_movk_i32 s15, 512
	global_load_dwordx2 v[120:121], v130, s[8:9]
	global_load_dwordx2 v[122:123], v130, s[8:9] offset:1024
	global_load_dword v124, v131, s[8:9]
	s_add_u32 s8, s8, 0x34000
	s_addc_u32 s9, s9, 0
	s_waitcnt vmcnt(0)
	v_lshlrev_b32_e32 v180, 16, v122
	v_and_b32_e32 v181, s69, v122
	v_lshlrev_b32_e32 v182, 16, v123
	v_and_b32_e32 v183, s69, v123
	s_cmp_eq_u32 s14, 0
	s_cbranch_scc1 .Lgla_st_join_1
	v_mul_f32_e32 v180, 0x3fb8aa3b, v180
	v_mul_f32_e32 v181, 0x3fb8aa3b, v181
	v_mul_f32_e32 v182, 0x3fb8aa3b, v182
	v_mul_f32_e32 v183, 0x3fb8aa3b, v183
.Lgla_st_join_1:
	v_lshlrev_b32_e32 v184, 16, v120
	v_and_b32_e32 v185, s69, v120
	v_lshlrev_b32_e32 v186, 16, v121
	v_and_b32_e32 v187, s69, v121
	v_lshlrev_b32_e32 v188, 16, v124
	v_and_b32_e32 v189, s69, v124
	ds_write_b128 v139, v[180:183] offset:8192
	ds_write_b128 v139, v[184:187] offset:17408
	ds_write2_b32 v140, v188, v189 offset1:4
	global_load_dwordx2 v[126:127], v130, s[8:9]
	global_load_dwordx2 v[190:191], v130, s[8:9] offset:1024
	global_load_dword v119, v131, s[8:9]
	s_add_u32 s8, s8, 0x34000
	s_addc_u32 s9, s9, 0
	global_load_dword v152, v131, s[8:9]
	global_load_dword v152, v131, s[8:9]
	global_load_dwordx2 v[120:121], v130, s[8:9]
	global_load_dwordx2 v[122:123], v130, s[8:9] offset:1024
	global_load_dword v124, v131, s[8:9]
	s_add_u32 s8, s8, 0x34000
	s_addc_u32 s9, s9, 0
	global_load_dword v152, v131, s[8:9]
	global_load_dword v152, v131, s[8:9]
	s_waitcnt lgkmcnt(0)
	s_barrier
	s_cmp_eq_u32 s14, 0
	s_cbranch_scc1 .Lgla_ret_setup
	v_and_b32_e32 v154, 15, v163
	v_bfe_u32 v155, v163, 4, 2
	v_lshrrev_b32_e32 v156, 6, v163
	v_mul_u32_u24_e32 v56, 528, v154
	v_lshl_add_u32 v56, v156, 6, v56
	v_lshl_add_u32 v56, v155, 4, v56
	v_mul_u32_u24_e32 v57, 528, v155
	v_lshl_add_u32 v57, v156, 6, v57
	v_lshl_add_u32 v57, v154, 2, v57
	v_lshrrev_b32_e32 v158, 1, v155
	v_and_b32_e32 v159, 1, v155
	v_lshlrev_b32_e32 v58, 8, v158
	v_lshl_add_u32 v58, v154, 4, v58
	v_lshl_add_u32 v58, v159, 3, v58
	v_mul_u32_u24_e32 v158, 1040, v154
	v_lshl_add_u32 v158, v156, 7, v158
	v_lshl_add_u32 v158, v155, 4, v158
	v_add_u32_e32 v59, 0x10000, v158
	v_add_u32_e32 v60, 0x14400, v158
	v_mul_u32_u24_e32 v158, 1280, v156
	v_add_u32_e32 v158, 0x19000, v158
	v_mul_u32_u24_e32 v61, 80, v154
	v_add_u32_e32 v61, v61, v158
	v_lshl_add_u32 v61, v155, 4, v61
	v_mul_u32_u24_e32 v62, 80, v155
	v_add_u32_e32 v62, v62, v158
	v_lshl_add_u32 v62, v154, 2, v62
	v_lshl_add_u32 v161, v155, 2, 0
	v_cmp_le_u32_e32 vcc, v161, v154
	s_nop 1
	v_cndmask_b32_e64 v48, 0, 1.0, vcc
	v_lshl_add_u32 v161, v155, 2, 1
	v_cmp_le_u32_e32 vcc, v161, v154
	s_nop 1
	v_cndmask_b32_e64 v49, 0, 1.0, vcc
	v_lshl_add_u32 v161, v155, 2, 2
	v_cmp_le_u32_e32 vcc, v161, v154
	s_nop 1
	v_cndmask_b32_e64 v50, 0, 1.0, vcc
	v_lshl_add_u32 v161, v155, 2, 3
	v_cmp_le_u32_e32 vcc, v161, v154
	s_nop 1
	v_cndmask_b32_e64 v51, 0, 1.0, vcc
	.p2align 6
.Lgla_loop_hgrn:
	ds_read_b128 v[20:23], v56 offset:17408
	ds_read_b128 v[24:27], v56 offset:8192
	ds_read_b64 v[32:33], v58 offset:26624
	ds_read_b64 v[34:35], v58 offset:27136
	ds_read_b64 v[36:37], v58 offset:27648
	ds_read_b64 v[38:39], v58 offset:28160
	ds_read2_b32 v[104:105], v150 offset0:0 offset1:32
	ds_read2_b32 v[106:107], v150 offset0:64 offset1:96
	ds_read2_b32 v[108:109], v150 offset0:128 offset1:160
	ds_read2_b32 v[110:111], v150 offset0:192 offset1:224
	s_waitcnt lgkmcnt(8)
	v_add_f32_dpp v68, v24, v24 row_shr:1 row_mask:0xf bank_mask:0xf bound_ctrl:0
	v_add_f32_dpp v69, v25, v25 row_shr:1 row_mask:0xf bank_mask:0xf bound_ctrl:0
	v_add_f32_dpp v70, v26, v26 row_shr:1 row_mask:0xf bank_mask:0xf bound_ctrl:0
	v_add_f32_dpp v71, v27, v27 row_shr:1 row_mask:0xf bank_mask:0xf bound_ctrl:0
	v_add_f32_dpp v72, v24, v24 row_shl:1 row_mask:0xf bank_mask:0xf bound_ctrl:0
	v_add_f32_dpp v73, v25, v25 row_shl:1 row_mask:0xf bank_mask:0xf bound_ctrl:0
	v_add_f32_dpp v74, v26, v26 row_shl:1 row_mask:0xf bank_mask:0xf bound_ctrl:0
	v_add_f32_dpp v75, v27, v27 row_shl:1 row_mask:0xf bank_mask:0xf bound_ctrl:0
	v_add_f32_dpp v68, v68, v68 row_shr:2 row_mask:0xf bank_mask:0xf bound_ctrl:0
	v_add_f32_dpp v69, v69, v69 row_shr:2 row_mask:0xf bank_mask:0xf bound_ctrl:0
	v_add_f32_dpp v70, v70, v70 row_shr:2 row_mask:0xf bank_mask:0xf bound_ctrl:0
	v_add_f32_dpp v71, v71, v71 row_shr:2 row_mask:0xf bank_mask:0xf bound_ctrl:0
	v_add_f32_dpp v72, v72, v72 row_shl:2 row_mask:0xf bank_mask:0xf bound_ctrl:0
	v_add_f32_dpp v73, v73, v73 row_shl:2 row_mask:0xf bank_mask:0xf bound_ctrl:0
	v_add_f32_dpp v74, v74, v74 row_shl:2 row_mask:0xf bank_mask:0xf bound_ctrl:0
	v_add_f32_dpp v75, v75, v75 row_shl:2 row_mask:0xf bank_mask:0xf bound_ctrl:0
	v_add_f32_dpp v68, v68, v68 row_shr:4 row_mask:0xf bank_mask:0xf bound_ctrl:0
	v_add_f32_dpp v69, v69, v69 row_shr:4 row_mask:0xf bank_mask:0xf bound_ctrl:0
	v_add_f32_dpp v70, v70, v70 row_shr:4 row_mask:0xf bank_mask:0xf bound_ctrl:0
	v_add_f32_dpp v71, v71, v71 row_shr:4 row_mask:0xf bank_mask:0xf bound_ctrl:0
	v_add_f32_dpp v72, v72, v72 row_shl:4 row_mask:0xf bank_mask:0xf bound_ctrl:0
	v_add_f32_dpp v73, v73, v73 row_shl:4 row_mask:0xf bank_mask:0xf bound_ctrl:0
	v_add_f32_dpp v74, v74, v74 row_shl:4 row_mask:0xf bank_mask:0xf bound_ctrl:0
	v_add_f32_dpp v75, v75, v75 row_shl:4 row_mask:0xf bank_mask:0xf bound_ctrl:0
	v_add_f32_dpp v68, v68, v68 row_shr:8 row_mask:0xf bank_mask:0xf bound_ctrl:0
	v_add_f32_dpp v69, v69, v69 row_shr:8 row_mask:0xf bank_mask:0xf bound_ctrl:0
	v_add_f32_dpp v70, v70, v70 row_shr:8 row_mask:0xf bank_mask:0xf bound_ctrl:0
	v_add_f32_dpp v71, v71, v71 row_shr:8 row_mask:0xf bank_mask:0xf bound_ctrl:0
	v_add_f32_dpp v72, v72, v72 row_shl:8 row_mask:0xf bank_mask:0xf bound_ctrl:0
	v_add_f32_dpp v73, v73, v73 row_shl:8 row_mask:0xf bank_mask:0xf bound_ctrl:0
	v_add_f32_dpp v74, v74, v74 row_shl:8 row_mask:0xf bank_mask:0xf bound_ctrl:0
	v_add_f32_dpp v75, v75, v75 row_shl:8 row_mask:0xf bank_mask:0xf bound_ctrl:0
	v_exp_f32_e32 v76, v24
	v_exp_f32_e32 v77, v25
	v_exp_f32_e32 v78, v26
	v_exp_f32_e32 v79, v27
	v_sub_f32_e32 v80, v72, v24
	v_sub_f32_e32 v81, v73, v25
	v_sub_f32_e32 v82, v74, v26
	v_sub_f32_e32 v83, v75, v27
	v_max_f32_e32 v80, 0xc2fc0000, v80
	v_max_f32_e32 v81, 0xc2fc0000, v81
	v_max_f32_e32 v82, 0xc2fc0000, v82
	v_max_f32_e32 v83, 0xc2fc0000, v83
	v_sub_f32_e32 v76, 1.0, v76
	v_sub_f32_e32 v77, 1.0, v77
	v_sub_f32_e32 v78, 1.0, v78
	v_sub_f32_e32 v79, 1.0, v79
	v_add_f32_e32 v92, v68, v80
	v_add_f32_e32 v93, v69, v81
	v_add_f32_e32 v94, v70, v82
	v_add_f32_e32 v95, v71, v83
	v_exp_f32_e32 v68, v68
	v_exp_f32_e32 v69, v69
	v_exp_f32_e32 v70, v70
	v_exp_f32_e32 v71, v71
	v_exp_f32_e64 v84, -v80
	v_exp_f32_e64 v85, -v81
	v_exp_f32_e64 v86, -v82
	v_exp_f32_e64 v87, -v83
	v_exp_f32_e32 v80, v80
	v_exp_f32_e32 v81, v81
	v_exp_f32_e32 v82, v82
	v_exp_f32_e32 v83, v83
	v_exp_f32_e32 v88, v92
	v_exp_f32_e32 v89, v93
	v_exp_f32_e32 v90, v94
	v_exp_f32_e32 v91, v95
	v_mul_f32_e32 v24, v76, v80
	v_mul_f32_e32 v25, v77, v81
	v_mul_f32_e32 v26, v78, v82
	v_mul_f32_e32 v27, v79, v83
	v_mul_f32_e32 v64, v20, v68
	v_mul_f32_e32 v65, v21, v69
	v_mul_f32_e32 v66, v22, v70
	v_mul_f32_e32 v67, v23, v71
	v_mul_f32_e32 v20, v20, v84
	v_mul_f32_e32 v21, v21, v85
	v_mul_f32_e32 v22, v22, v86
	v_mul_f32_e32 v23, v23, v87
	ds_write_b128 v61, v[24:27]
	ds_read_b32 v28, v62 offset:0
	ds_read_b32 v29, v62 offset:320
	ds_read_b32 v30, v62 offset:640
	ds_read_b32 v31, v62 offset:960
	v_mfma_f32_16x16x4_f32 v[16:19], v24, v20, 0
	s_waitcnt vmcnt(7)
	v_lshlrev_b32_e32 v180, 16, v190
	v_and_b32_e32 v181, s69, v190
	v_mfma_f32_16x16x4_f32 v[8:11], v0, v64, 0
	v_lshlrev_b32_e32 v182, 16, v191
	v_and_b32_e32 v183, s69, v191
	v_lshlrev_b32_e32 v184, 16, v126
	v_mfma_f32_16x16x4_f32 v[16:19], v25, v21, v[16:19]
	v_and_b32_e32 v185, s69, v126
	v_lshlrev_b32_e32 v186, 16, v127
	v_and_b32_e32 v187, s69, v127
	v_mfma_f32_16x16x4_f32 v[12:15], v4, v64, 0
	v_lshlrev_b32_e32 v188, 16, v119
	v_and_b32_e32 v189, s69, v119
	v_mul_f32_e32 v180, 0x3fb8aa3b, v180
	v_mfma_f32_16x16x4_f32 v[16:19], v26, v22, v[16:19]
	v_mul_f32_e32 v181, 0x3fb8aa3b, v181
	v_mul_f32_e32 v182, 0x3fb8aa3b, v182
	v_mul_f32_e32 v183, 0x3fb8aa3b, v183
	v_mfma_f32_16x16x4_f32 v[8:11], v1, v65, v[8:11]
	ds_write_b128 v139, v[180:183] offset:40960
	ds_write_b128 v139, v[184:187] offset:50176
	ds_write2_b32 v153, v188, v189 offset1:4
	v_mfma_f32_16x16x4_f32 v[16:19], v27, v23, v[16:19]
	global_load_dwordx2 v[126:127], v130, s[8:9]
	global_load_dwordx2 v[190:191], v130, s[8:9] offset:1024
	global_load_dword v119, v131, s[8:9]
	s_add_u32 s8, s8, 0x34000
	s_addc_u32 s9, s9, 0
	v_mfma_f32_16x16x4_f32 v[12:15], v5, v65, v[12:15]
	s_waitcnt lgkmcnt(8)
	v_add_f32_e32 v112, v104, v105
	v_add_f32_e32 v112, v112, v106
	v_mfma_f32_16x16x4_f32 v[8:11], v2, v66, v[8:11]
	v_add_f32_e32 v112, v112, v107
	v_add_f32_e32 v112, v112, v108
	v_add_f32_e32 v112, v112, v109
	v_mfma_f32_16x16x4_f32 v[12:15], v6, v66, v[12:15]
	v_add_f32_e32 v112, v112, v110
	v_add_f32_e32 v112, v112, v111
	v_mul_f32_e32 v113, v112, v112
	v_mfma_f32_16x16x4_f32 v[8:11], v3, v67, v[8:11]
	v_cvt_pk_bf16_f32 v116, v112, v129
	v_mov_b32_e32 v117, v112
	v_mov_b32_e32 v118, v113
	v_mfma_f32_16x16x4_f32 v[12:15], v7, v67, v[12:15]
	global_store_short v132, v116, s[10:11]
	s_nop 1
	v_permlane16_swap_b32_e32 v112, v117
	v_permlane16_swap_b32_e32 v113, v118
	s_waitcnt lgkmcnt(3)
	v_pk_mul_f32 v[0:1], v[0:1], v[88:89]
	v_pk_mul_f32 v[2:3], v[2:3], v[90:91]
	v_pk_mul_f32 v[4:5], v[4:5], v[88:89]
	v_pk_mul_f32 v[6:7], v[6:7], v[90:91]
	v_pk_mul_f32 v[16:17], v[16:17], v[48:49]
	v_pk_mul_f32 v[18:19], v[18:19], v[50:51]
	s_nop 1
	v_permlane16_swap_b32_e32 v16, v17
	v_permlane16_swap_b32_e32 v18, v19
	s_nop 1
	v_permlane32_swap_b32_e32 v16, v18
	v_permlane32_swap_b32_e32 v17, v19
	s_nop 1
	v_mfma_f32_16x16x4_f32 v[8:11], v32, v16, v[8:11]
	v_add_f32_e32 v112, v112, v117
	v_add_f32_e32 v113, v113, v118
	s_nop 1
	v_add_f32_dpp v112, v112, v112 row_ror:8 row_mask:0xf bank_mask:0xf
	v_mfma_f32_16x16x4_f32 v[12:15], v33, v16, v[12:15]
	v_add_f32_dpp v113, v113, v113 row_ror:8 row_mask:0xf bank_mask:0xf
	s_nop 1
	v_add_f32_dpp v112, v112, v112 row_ror:4 row_mask:0xf bank_mask:0xf
	v_add_f32_dpp v113, v113, v113 row_ror:4 row_mask:0xf bank_mask:0xf
	v_mfma_f32_16x16x4_f32 v[8:11], v34, v17, v[8:11]
	s_nop 1
	v_add_f32_dpp v112, v112, v112 row_ror:2 row_mask:0xf bank_mask:0xf
	v_add_f32_dpp v113, v113, v113 row_ror:2 row_mask:0xf bank_mask:0xf
	s_nop 1
	v_add_f32_dpp v112, v112, v112 row_ror:1 row_mask:0xf bank_mask:0xf
	v_mfma_f32_16x16x4_f32 v[12:15], v35, v17, v[12:15]
	v_add_f32_dpp v113, v113, v113 row_ror:1 row_mask:0xf bank_mask:0xf
	v_mov_b32_e32 v114, 0
	v_mov_b32_e32 v115, 0
	v_mfma_f32_16x16x4_f32 v[8:11], v36, v18, v[8:11]
	s_nop 0
	s_mov_b64 exec, s[18:19]
	global_store_dwordx4 v133, v[112:115], s[12:13]
	s_mov_b64 exec, -1
	s_cmp_eq_u32 s15, 512
	s_cselect_b32 s20, 0, 0x10000
	s_cselect_b32 s21, 0, 0x1000
	s_add_u32 s10, s10, s20
	s_addc_u32 s11, s11, 0
	s_add_u32 s12, s12, s21
	s_addc_u32 s13, s13, 0
	v_mfma_f32_16x16x4_f32 v[12:15], v37, v18, v[12:15]
	v_mfma_f32_16x16x4_f32 v[8:11], v38, v19, v[8:11]
	v_mfma_f32_16x16x4_f32 v[12:15], v39, v19, v[12:15]
	v_mfma_f32_16x16x4_f32 v[0:3], v28, v32, v[0:3]
	v_mfma_f32_16x16x4_f32 v[4:7], v28, v33, v[4:7]
	v_mfma_f32_16x16x4_f32 v[0:3], v29, v34, v[0:3]
	v_mfma_f32_16x16x4_f32 v[4:7], v29, v35, v[4:7]
	v_mfma_f32_16x16x4_f32 v[0:3], v30, v36, v[0:3]
	v_mfma_f32_16x16x4_f32 v[4:7], v30, v37, v[4:7]
	v_mfma_f32_16x16x4_f32 v[0:3], v31, v38, v[0:3]
	v_mfma_f32_16x16x4_f32 v[4:7], v31, v39, v[4:7]
	s_nop 1
	ds_write_b128 v59, v[8:11]
	ds_write_b128 v59, v[12:15] offset:64
	s_sub_u32 s15, s15, 1
	s_waitcnt lgkmcnt(0)
	s_barrier
	ds_read_b128 v[20:23], v56 offset:50176
	ds_read_b128 v[24:27], v56 offset:40960
	ds_read_b64 v[32:33], v58 offset:59392
	ds_read_b64 v[34:35], v58 offset:59904
	ds_read_b64 v[36:37], v58 offset:60416
	ds_read_b64 v[38:39], v58 offset:60928
	ds_read2_b32 v[104:105], v149 offset0:0 offset1:32
	ds_read2_b32 v[106:107], v149 offset0:64 offset1:96
	ds_read2_b32 v[108:109], v149 offset0:128 offset1:160
	ds_read2_b32 v[110:111], v149 offset0:192 offset1:224
	s_waitcnt lgkmcnt(8)
	v_add_f32_dpp v68, v24, v24 row_shr:1 row_mask:0xf bank_mask:0xf bound_ctrl:0
	v_add_f32_dpp v69, v25, v25 row_shr:1 row_mask:0xf bank_mask:0xf bound_ctrl:0
	v_add_f32_dpp v70, v26, v26 row_shr:1 row_mask:0xf bank_mask:0xf bound_ctrl:0
	v_add_f32_dpp v71, v27, v27 row_shr:1 row_mask:0xf bank_mask:0xf bound_ctrl:0
	v_add_f32_dpp v72, v24, v24 row_shl:1 row_mask:0xf bank_mask:0xf bound_ctrl:0
	v_add_f32_dpp v73, v25, v25 row_shl:1 row_mask:0xf bank_mask:0xf bound_ctrl:0
	v_add_f32_dpp v74, v26, v26 row_shl:1 row_mask:0xf bank_mask:0xf bound_ctrl:0
	v_add_f32_dpp v75, v27, v27 row_shl:1 row_mask:0xf bank_mask:0xf bound_ctrl:0
	v_add_f32_dpp v68, v68, v68 row_shr:2 row_mask:0xf bank_mask:0xf bound_ctrl:0
	v_add_f32_dpp v69, v69, v69 row_shr:2 row_mask:0xf bank_mask:0xf bound_ctrl:0
	v_add_f32_dpp v70, v70, v70 row_shr:2 row_mask:0xf bank_mask:0xf bound_ctrl:0
	v_add_f32_dpp v71, v71, v71 row_shr:2 row_mask:0xf bank_mask:0xf bound_ctrl:0
	v_add_f32_dpp v72, v72, v72 row_shl:2 row_mask:0xf bank_mask:0xf bound_ctrl:0
	v_add_f32_dpp v73, v73, v73 row_shl:2 row_mask:0xf bank_mask:0xf bound_ctrl:0
	v_add_f32_dpp v74, v74, v74 row_shl:2 row_mask:0xf bank_mask:0xf bound_ctrl:0
	v_add_f32_dpp v75, v75, v75 row_shl:2 row_mask:0xf bank_mask:0xf bound_ctrl:0
	v_add_f32_dpp v68, v68, v68 row_shr:4 row_mask:0xf bank_mask:0xf bound_ctrl:0
	v_add_f32_dpp v69, v69, v69 row_shr:4 row_mask:0xf bank_mask:0xf bound_ctrl:0
	v_add_f32_dpp v70, v70, v70 row_shr:4 row_mask:0xf bank_mask:0xf bound_ctrl:0
	v_add_f32_dpp v71, v71, v71 row_shr:4 row_mask:0xf bank_mask:0xf bound_ctrl:0
	v_add_f32_dpp v72, v72, v72 row_shl:4 row_mask:0xf bank_mask:0xf bound_ctrl:0
	v_add_f32_dpp v73, v73, v73 row_shl:4 row_mask:0xf bank_mask:0xf bound_ctrl:0
	v_add_f32_dpp v74, v74, v74 row_shl:4 row_mask:0xf bank_mask:0xf bound_ctrl:0
	v_add_f32_dpp v75, v75, v75 row_shl:4 row_mask:0xf bank_mask:0xf bound_ctrl:0
	v_add_f32_dpp v68, v68, v68 row_shr:8 row_mask:0xf bank_mask:0xf bound_ctrl:0
	v_add_f32_dpp v69, v69, v69 row_shr:8 row_mask:0xf bank_mask:0xf bound_ctrl:0
	v_add_f32_dpp v70, v70, v70 row_shr:8 row_mask:0xf bank_mask:0xf bound_ctrl:0
	v_add_f32_dpp v71, v71, v71 row_shr:8 row_mask:0xf bank_mask:0xf bound_ctrl:0
	v_add_f32_dpp v72, v72, v72 row_shl:8 row_mask:0xf bank_mask:0xf bound_ctrl:0
	v_add_f32_dpp v73, v73, v73 row_shl:8 row_mask:0xf bank_mask:0xf bound_ctrl:0
	v_add_f32_dpp v74, v74, v74 row_shl:8 row_mask:0xf bank_mask:0xf bound_ctrl:0
	v_add_f32_dpp v75, v75, v75 row_shl:8 row_mask:0xf bank_mask:0xf bound_ctrl:0
	v_exp_f32_e32 v76, v24
	v_exp_f32_e32 v77, v25
	v_exp_f32_e32 v78, v26
	v_exp_f32_e32 v79, v27
	v_sub_f32_e32 v80, v72, v24
	v_sub_f32_e32 v81, v73, v25
	v_sub_f32_e32 v82, v74, v26
	v_sub_f32_e32 v83, v75, v27
	v_max_f32_e32 v80, 0xc2fc0000, v80
	v_max_f32_e32 v81, 0xc2fc0000, v81
	v_max_f32_e32 v82, 0xc2fc0000, v82
	v_max_f32_e32 v83, 0xc2fc0000, v83
	v_sub_f32_e32 v76, 1.0, v76
	v_sub_f32_e32 v77, 1.0, v77
	v_sub_f32_e32 v78, 1.0, v78
	v_sub_f32_e32 v79, 1.0, v79
	v_add_f32_e32 v92, v68, v80
	v_add_f32_e32 v93, v69, v81
	v_add_f32_e32 v94, v70, v82
	v_add_f32_e32 v95, v71, v83
	v_exp_f32_e32 v68, v68
	v_exp_f32_e32 v69, v69
	v_exp_f32_e32 v70, v70
	v_exp_f32_e32 v71, v71
	v_exp_f32_e64 v84, -v80
	v_exp_f32_e64 v85, -v81
	v_exp_f32_e64 v86, -v82
	v_exp_f32_e64 v87, -v83
	v_exp_f32_e32 v80, v80
	v_exp_f32_e32 v81, v81
	v_exp_f32_e32 v82, v82
	v_exp_f32_e32 v83, v83
	v_exp_f32_e32 v88, v92
	v_exp_f32_e32 v89, v93
	v_exp_f32_e32 v90, v94
	v_exp_f32_e32 v91, v95
	v_mul_f32_e32 v24, v76, v80
	v_mul_f32_e32 v25, v77, v81
	v_mul_f32_e32 v26, v78, v82
	v_mul_f32_e32 v27, v79, v83
	v_mul_f32_e32 v64, v20, v68
	v_mul_f32_e32 v65, v21, v69
	v_mul_f32_e32 v66, v22, v70
	v_mul_f32_e32 v67, v23, v71
	v_mul_f32_e32 v20, v20, v84
	v_mul_f32_e32 v21, v21, v85
	v_mul_f32_e32 v22, v22, v86
	v_mul_f32_e32 v23, v23, v87
	ds_write_b128 v61, v[24:27]
	ds_read_b32 v28, v62 offset:0
	ds_read_b32 v29, v62 offset:320
	ds_read_b32 v30, v62 offset:640
	ds_read_b32 v31, v62 offset:960
	v_mfma_f32_16x16x4_f32 v[16:19], v24, v20, 0
	s_waitcnt vmcnt(7)
	v_lshlrev_b32_e32 v180, 16, v122
	v_and_b32_e32 v181, s69, v122
	v_mfma_f32_16x16x4_f32 v[8:11], v0, v64, 0
	v_lshlrev_b32_e32 v182, 16, v123
	v_and_b32_e32 v183, s69, v123
	v_lshlrev_b32_e32 v184, 16, v120
	v_mfma_f32_16x16x4_f32 v[16:19], v25, v21, v[16:19]
	v_and_b32_e32 v185, s69, v120
	v_lshlrev_b32_e32 v186, 16, v121
	v_and_b32_e32 v187, s69, v121
	v_mfma_f32_16x16x4_f32 v[12:15], v4, v64, 0
	v_lshlrev_b32_e32 v188, 16, v124
	v_and_b32_e32 v189, s69, v124
	v_mul_f32_e32 v180, 0x3fb8aa3b, v180
	v_mfma_f32_16x16x4_f32 v[16:19], v26, v22, v[16:19]
	v_mul_f32_e32 v181, 0x3fb8aa3b, v181
	v_mul_f32_e32 v182, 0x3fb8aa3b, v182
	v_mul_f32_e32 v183, 0x3fb8aa3b, v183
	v_mfma_f32_16x16x4_f32 v[8:11], v1, v65, v[8:11]
	ds_write_b128 v139, v[180:183] offset:8192
	ds_write_b128 v139, v[184:187] offset:17408
	ds_write2_b32 v140, v188, v189 offset1:4
	v_mfma_f32_16x16x4_f32 v[16:19], v27, v23, v[16:19]
	global_load_dwordx2 v[120:121], v130, s[8:9]
	global_load_dwordx2 v[122:123], v130, s[8:9] offset:1024
	global_load_dword v124, v131, s[8:9]
	s_add_u32 s8, s8, 0x34000
	s_addc_u32 s9, s9, 0
	v_mfma_f32_16x16x4_f32 v[12:15], v5, v65, v[12:15]
	s_waitcnt lgkmcnt(8)
	v_add_f32_e32 v112, v104, v105
	v_add_f32_e32 v112, v112, v106
	v_mfma_f32_16x16x4_f32 v[8:11], v2, v66, v[8:11]
	v_add_f32_e32 v112, v112, v107
	v_add_f32_e32 v112, v112, v108
	v_add_f32_e32 v112, v112, v109
	v_mfma_f32_16x16x4_f32 v[12:15], v6, v66, v[12:15]
	v_add_f32_e32 v112, v112, v110
	v_add_f32_e32 v112, v112, v111
	v_mul_f32_e32 v113, v112, v112
	v_mfma_f32_16x16x4_f32 v[8:11], v3, v67, v[8:11]
	v_cvt_pk_bf16_f32 v116, v112, v129
	v_mov_b32_e32 v117, v112
	v_mov_b32_e32 v118, v113
	v_mfma_f32_16x16x4_f32 v[12:15], v7, v67, v[12:15]
	global_store_short v132, v116, s[10:11]
	s_nop 1
	v_permlane16_swap_b32_e32 v112, v117
	v_permlane16_swap_b32_e32 v113, v118
	s_waitcnt lgkmcnt(3)
	v_pk_mul_f32 v[0:1], v[0:1], v[88:89]
	v_pk_mul_f32 v[2:3], v[2:3], v[90:91]
	v_pk_mul_f32 v[4:5], v[4:5], v[88:89]
	v_pk_mul_f32 v[6:7], v[6:7], v[90:91]
	v_pk_mul_f32 v[16:17], v[16:17], v[48:49]
	v_pk_mul_f32 v[18:19], v[18:19], v[50:51]
	s_nop 1
	v_permlane16_swap_b32_e32 v16, v17
	v_permlane16_swap_b32_e32 v18, v19
	s_nop 1
	v_permlane32_swap_b32_e32 v16, v18
	v_permlane32_swap_b32_e32 v17, v19
	s_nop 1
	v_mfma_f32_16x16x4_f32 v[8:11], v32, v16, v[8:11]
	v_add_f32_e32 v112, v112, v117
	v_add_f32_e32 v113, v113, v118
	s_nop 1
	v_add_f32_dpp v112, v112, v112 row_ror:8 row_mask:0xf bank_mask:0xf
	v_mfma_f32_16x16x4_f32 v[12:15], v33, v16, v[12:15]
	v_add_f32_dpp v113, v113, v113 row_ror:8 row_mask:0xf bank_mask:0xf
	s_nop 1
	v_add_f32_dpp v112, v112, v112 row_ror:4 row_mask:0xf bank_mask:0xf
	v_add_f32_dpp v113, v113, v113 row_ror:4 row_mask:0xf bank_mask:0xf
	v_mfma_f32_16x16x4_f32 v[8:11], v34, v17, v[8:11]
	s_nop 1
	v_add_f32_dpp v112, v112, v112 row_ror:2 row_mask:0xf bank_mask:0xf
	v_add_f32_dpp v113, v113, v113 row_ror:2 row_mask:0xf bank_mask:0xf
	s_nop 1
	v_add_f32_dpp v112, v112, v112 row_ror:1 row_mask:0xf bank_mask:0xf
	v_mfma_f32_16x16x4_f32 v[12:15], v35, v17, v[12:15]
	v_add_f32_dpp v113, v113, v113 row_ror:1 row_mask:0xf bank_mask:0xf
	v_mov_b32_e32 v114, 0
	v_mov_b32_e32 v115, 0
	v_mfma_f32_16x16x4_f32 v[8:11], v36, v18, v[8:11]
	s_nop 0
	s_mov_b64 exec, s[18:19]
	global_store_dwordx4 v133, v[112:115], s[12:13]
	s_mov_b64 exec, -1
	s_cmp_eq_u32 s15, 512
	s_cselect_b32 s20, 0, 0x10000
	s_cselect_b32 s21, 0, 0x1000
	s_add_u32 s10, s10, s20
	s_addc_u32 s11, s11, 0
	s_add_u32 s12, s12, s21
	s_addc_u32 s13, s13, 0
	v_mfma_f32_16x16x4_f32 v[12:15], v37, v18, v[12:15]
	v_mfma_f32_16x16x4_f32 v[8:11], v38, v19, v[8:11]
	v_mfma_f32_16x16x4_f32 v[12:15], v39, v19, v[12:15]
	v_mfma_f32_16x16x4_f32 v[0:3], v28, v32, v[0:3]
	v_mfma_f32_16x16x4_f32 v[4:7], v28, v33, v[4:7]
	v_mfma_f32_16x16x4_f32 v[0:3], v29, v34, v[0:3]
	v_mfma_f32_16x16x4_f32 v[4:7], v29, v35, v[4:7]
	v_mfma_f32_16x16x4_f32 v[0:3], v30, v36, v[0:3]
	v_mfma_f32_16x16x4_f32 v[4:7], v30, v37, v[4:7]
	v_mfma_f32_16x16x4_f32 v[0:3], v31, v38, v[0:3]
	v_mfma_f32_16x16x4_f32 v[4:7], v31, v39, v[4:7]
	s_nop 1
	ds_write_b128 v60, v[8:11]
	ds_write_b128 v60, v[12:15] offset:64
	s_sub_u32 s15, s15, 1
	s_waitcnt lgkmcnt(0)
	s_barrier
	s_cmp_lg_u32 s15, 0
	s_cbranch_scc1 .Lgla_loop_hgrn
	s_branch .Lgla_tail
.Lgla_ret_setup:
	v_and_b32_e32 v154, 15, v163
	v_bfe_u32 v155, v163, 4, 2
	v_lshrrev_b32_e32 v156, 6, v163
	v_mul_u32_u24_e32 v56, 528, v154
	v_lshl_add_u32 v56, v156, 6, v56
	v_lshl_add_u32 v56, v155, 4, v56
	v_mul_u32_u24_e32 v57, 528, v155
	v_lshl_add_u32 v57, v156, 6, v57
	v_lshl_add_u32 v57, v154, 2, v57
	v_lshrrev_b32_e32 v158, 1, v155
	v_and_b32_e32 v159, 1, v155
	v_lshlrev_b32_e32 v58, 8, v158
	v_lshl_add_u32 v58, v154, 4, v58
	v_lshl_add_u32 v58, v159, 3, v58
	v_mul_u32_u24_e32 v158, 1040, v154
	v_lshl_add_u32 v158, v156, 7, v158
	v_lshl_add_u32 v158, v155, 4, v158
	v_add_u32_e32 v59, 0x10000, v158
	v_add_u32_e32 v60, 0x14400, v158
	v_log_f32_e32 v157, v100
	v_add_u32_e32 v160, 1, v154
	v_cvt_f32_i32_e32 v160, v160
	v_mul_f32_e32 v160, v160, v157
	v_exp_f32_e32 v40, v160
	s_nop 0
	v_mov_b32_e32 v41, v40
	v_sub_u32_e32 v160, 15, v155
	v_cvt_f32_i32_e32 v160, v160
	v_mul_f32_e32 v160, v160, v157
	v_exp_f32_e32 v44, v160
	v_sub_u32_e32 v160, 11, v155
	v_cvt_f32_i32_e32 v160, v160
	v_mul_f32_e32 v160, v160, v157
	v_exp_f32_e32 v45, v160
	v_sub_u32_e32 v160, 7, v155
	v_cvt_f32_i32_e32 v160, v160
	v_mul_f32_e32 v160, v160, v157
	v_exp_f32_e32 v46, v160
	v_sub_u32_e32 v160, 3, v155
	v_cvt_f32_i32_e32 v160, v160
	v_mul_f32_e32 v160, v160, v157
	v_exp_f32_e32 v47, v160
	v_lshl_add_u32 v161, v155, 2, 0
	v_add_u32_e32 v160, 1, v161
	v_cvt_f32_i32_e32 v160, v160
	v_mul_f32_e64 v160, -v160, v157
	v_exp_f32_e32 v160, v160
	v_cmp_le_u32_e32 vcc, v161, v154
	s_nop 1
	v_cndmask_b32_e32 v48, 0, v160, vcc
	v_lshl_add_u32 v161, v155, 2, 1
	v_add_u32_e32 v160, 1, v161
	v_cvt_f32_i32_e32 v160, v160
	v_mul_f32_e64 v160, -v160, v157
	v_exp_f32_e32 v160, v160
	v_cmp_le_u32_e32 vcc, v161, v154
	s_nop 1
	v_cndmask_b32_e32 v49, 0, v160, vcc
	v_lshl_add_u32 v161, v155, 2, 2
	v_add_u32_e32 v160, 1, v161
	v_cvt_f32_i32_e32 v160, v160
	v_mul_f32_e64 v160, -v160, v157
	v_exp_f32_e32 v160, v160
	v_cmp_le_u32_e32 vcc, v161, v154
	s_nop 1
	v_cndmask_b32_e32 v50, 0, v160, vcc
	v_lshl_add_u32 v161, v155, 2, 3
	v_add_u32_e32 v160, 1, v161
	v_cvt_f32_i32_e32 v160, v160
	v_mul_f32_e64 v160, -v160, v157
	v_exp_f32_e32 v160, v160
	v_cmp_le_u32_e32 vcc, v161, v154
	s_nop 1
	v_cndmask_b32_e32 v51, 0, v160, vcc
	v_mul_f32_e32 v52, v100, v100
	v_mul_f32_e32 v52, v52, v52
	v_mul_f32_e32 v52, v52, v52
	v_mul_f32_e32 v52, v52, v52
	v_mov_b32_e32 v53, v52
	.p2align 6
.Lgla_loop_ret:
	ds_read_b128 v[20:23], v56 offset:17408
	ds_read_b128 v[24:27], v56 offset:8192
	ds_read_b32 v28, v57 offset:8192
	ds_read_b32 v29, v57 offset:10304
	ds_read_b32 v30, v57 offset:12416
	ds_read_b32 v31, v57 offset:14528
	ds_read_b64 v[32:33], v58 offset:26624
	ds_read_b64 v[34:35], v58 offset:27136
	ds_read_b64 v[36:37], v58 offset:27648
	ds_read_b64 v[38:39], v58 offset:28160
	ds_read2_b32 v[104:105], v150 offset0:0 offset1:32
	ds_read2_b32 v[106:107], v150 offset0:64 offset1:96
	ds_read2_b32 v[108:109], v150 offset0:128 offset1:160
	ds_read2_b32 v[110:111], v150 offset0:192 offset1:224
	s_waitcnt lgkmcnt(12)
	v_pk_mul_f32 v[20:21], v[20:21], v[40:41]
	v_pk_mul_f32 v[22:23], v[22:23], v[40:41]
	s_nop 1
	v_mfma_f32_16x16x4_f32 v[16:19], v24, v20, 0
	s_waitcnt vmcnt(7)
	v_lshlrev_b32_e32 v180, 16, v190
	v_and_b32_e32 v181, s69, v190
	v_mfma_f32_16x16x4_f32 v[8:11], v0, v20, 0
	v_lshlrev_b32_e32 v182, 16, v191
	v_and_b32_e32 v183, s69, v191
	v_lshlrev_b32_e32 v184, 16, v126
	v_mfma_f32_16x16x4_f32 v[16:19], v25, v21, v[16:19]
	v_and_b32_e32 v185, s69, v126
	v_lshlrev_b32_e32 v186, 16, v127
	v_and_b32_e32 v187, s69, v127
	v_mfma_f32_16x16x4_f32 v[12:15], v4, v20, 0
	v_lshlrev_b32_e32 v188, 16, v119
	v_and_b32_e32 v189, s69, v119
	ds_write_b128 v139, v[180:183] offset:40960
	v_mfma_f32_16x16x4_f32 v[16:19], v26, v22, v[16:19]
	ds_write_b128 v139, v[184:187] offset:50176
	ds_write2_b32 v153, v188, v189 offset1:4
	global_load_dwordx2 v[126:127], v130, s[8:9]
	v_mfma_f32_16x16x4_f32 v[8:11], v1, v21, v[8:11]
	global_load_dwordx2 v[190:191], v130, s[8:9] offset:1024
	global_load_dword v119, v131, s[8:9]
	s_add_u32 s8, s8, 0x34000
	s_addc_u32 s9, s9, 0
	s_waitcnt lgkmcnt(3)
	v_mfma_f32_16x16x4_f32 v[16:19], v27, v23, v[16:19]
	v_add_f32_e32 v112, v104, v105
	v_add_f32_e32 v112, v112, v106
	v_add_f32_e32 v112, v112, v107
	v_mfma_f32_16x16x4_f32 v[12:15], v5, v21, v[12:15]
	v_add_f32_e32 v112, v112, v108
	v_add_f32_e32 v112, v112, v109
	v_add_f32_e32 v112, v112, v110
	v_mfma_f32_16x16x4_f32 v[8:11], v2, v22, v[8:11]
	v_add_f32_e32 v112, v112, v111
	v_mul_f32_e32 v113, v112, v112
	v_cvt_pk_bf16_f32 v116, v112, v129
	v_mfma_f32_16x16x4_f32 v[12:15], v6, v22, v[12:15]
	v_mov_b32_e32 v117, v112
	v_mov_b32_e32 v118, v113
	global_store_short v132, v116, s[10:11]
	v_mfma_f32_16x16x4_f32 v[8:11], v3, v23, v[8:11]
	s_nop 1
	v_permlane16_swap_b32_e32 v112, v117
	v_permlane16_swap_b32_e32 v113, v118
	v_add_f32_e32 v112, v112, v117
	v_mfma_f32_16x16x4_f32 v[12:15], v7, v23, v[12:15]
	v_add_f32_e32 v113, v113, v118
	s_nop 1
	v_add_f32_dpp v112, v112, v112 row_ror:8 row_mask:0xf bank_mask:0xf
	v_add_f32_dpp v113, v113, v113 row_ror:8 row_mask:0xf bank_mask:0xf
	s_waitcnt lgkmcnt(7)
	v_mul_f32_e32 v28, v28, v44
	v_mul_f32_e32 v29, v29, v45
	v_mul_f32_e32 v30, v30, v46
	v_mul_f32_e32 v31, v31, v47
	v_pk_mul_f32 v[0:1], v[0:1], v[52:53]
	v_pk_mul_f32 v[2:3], v[2:3], v[52:53]
	v_pk_mul_f32 v[4:5], v[4:5], v[52:53]
	v_pk_mul_f32 v[6:7], v[6:7], v[52:53]
	v_pk_mul_f32 v[16:17], v[16:17], v[48:49]
	v_pk_mul_f32 v[18:19], v[18:19], v[50:51]
	s_nop 1
	v_permlane16_swap_b32_e32 v16, v17
	v_permlane16_swap_b32_e32 v18, v19
	s_nop 1
	v_permlane32_swap_b32_e32 v16, v18
	v_permlane32_swap_b32_e32 v17, v19
	s_nop 1
	v_mfma_f32_16x16x4_f32 v[8:11], v32, v16, v[8:11]
	s_nop 1
	v_add_f32_dpp v112, v112, v112 row_ror:4 row_mask:0xf bank_mask:0xf
	v_add_f32_dpp v113, v113, v113 row_ror:4 row_mask:0xf bank_mask:0xf
	s_nop 1
	v_add_f32_dpp v112, v112, v112 row_ror:2 row_mask:0xf bank_mask:0xf
	v_mfma_f32_16x16x4_f32 v[12:15], v33, v16, v[12:15]
	v_add_f32_dpp v113, v113, v113 row_ror:2 row_mask:0xf bank_mask:0xf
	s_nop 1
	v_add_f32_dpp v112, v112, v112 row_ror:1 row_mask:0xf bank_mask:0xf
	v_add_f32_dpp v113, v113, v113 row_ror:1 row_mask:0xf bank_mask:0xf
	v_mfma_f32_16x16x4_f32 v[8:11], v34, v17, v[8:11]
	v_mov_b32_e32 v114, 0
	v_mov_b32_e32 v115, 0
	s_nop 0
	s_mov_b64 exec, s[18:19]
	global_store_dwordx4 v133, v[112:115], s[12:13]
	s_mov_b64 exec, -1
	s_cmp_eq_u32 s15, 512
	s_cselect_b32 s20, 0, 0x10000
	s_cselect_b32 s21, 0, 0x1000
	s_add_u32 s10, s10, s20
	s_addc_u32 s11, s11, 0
	s_add_u32 s12, s12, s21
	s_addc_u32 s13, s13, 0
	v_mfma_f32_16x16x4_f32 v[12:15], v35, v17, v[12:15]
	v_mfma_f32_16x16x4_f32 v[8:11], v36, v18, v[8:11]
	v_mfma_f32_16x16x4_f32 v[12:15], v37, v18, v[12:15]
	v_mfma_f32_16x16x4_f32 v[8:11], v38, v19, v[8:11]
	v_mfma_f32_16x16x4_f32 v[12:15], v39, v19, v[12:15]
	v_mfma_f32_16x16x4_f32 v[0:3], v28, v32, v[0:3]
	v_mfma_f32_16x16x4_f32 v[4:7], v28, v33, v[4:7]
	v_mfma_f32_16x16x4_f32 v[0:3], v29, v34, v[0:3]
	v_mfma_f32_16x16x4_f32 v[4:7], v29, v35, v[4:7]
	v_mfma_f32_16x16x4_f32 v[0:3], v30, v36, v[0:3]
	v_mfma_f32_16x16x4_f32 v[4:7], v30, v37, v[4:7]
	v_mfma_f32_16x16x4_f32 v[0:3], v31, v38, v[0:3]
	v_mfma_f32_16x16x4_f32 v[4:7], v31, v39, v[4:7]
	s_nop 1
	ds_write_b128 v59, v[8:11]
	ds_write_b128 v59, v[12:15] offset:64
	s_sub_u32 s15, s15, 1
	s_waitcnt lgkmcnt(0)
	s_barrier
	ds_read_b128 v[20:23], v56 offset:50176
	ds_read_b128 v[24:27], v56 offset:40960
	ds_read_b32 v28, v57 offset:40960
	ds_read_b32 v29, v57 offset:43072
	ds_read_b32 v30, v57 offset:45184
	ds_read_b32 v31, v57 offset:47296
	ds_read_b64 v[32:33], v58 offset:59392
	ds_read_b64 v[34:35], v58 offset:59904
	ds_read_b64 v[36:37], v58 offset:60416
	ds_read_b64 v[38:39], v58 offset:60928
	ds_read2_b32 v[104:105], v149 offset0:0 offset1:32
	ds_read2_b32 v[106:107], v149 offset0:64 offset1:96
	ds_read2_b32 v[108:109], v149 offset0:128 offset1:160
	ds_read2_b32 v[110:111], v149 offset0:192 offset1:224
	s_waitcnt lgkmcnt(12)
	v_pk_mul_f32 v[20:21], v[20:21], v[40:41]
	v_pk_mul_f32 v[22:23], v[22:23], v[40:41]
	s_nop 1
	v_mfma_f32_16x16x4_f32 v[16:19], v24, v20, 0
	s_waitcnt vmcnt(7)
	v_lshlrev_b32_e32 v180, 16, v122
	v_and_b32_e32 v181, s69, v122
	v_mfma_f32_16x16x4_f32 v[8:11], v0, v20, 0
	v_lshlrev_b32_e32 v182, 16, v123
	v_and_b32_e32 v183, s69, v123
	v_lshlrev_b32_e32 v184, 16, v120
	v_mfma_f32_16x16x4_f32 v[16:19], v25, v21, v[16:19]
	v_and_b32_e32 v185, s69, v120
	v_lshlrev_b32_e32 v186, 16, v121
	v_and_b32_e32 v187, s69, v121
	v_mfma_f32_16x16x4_f32 v[12:15], v4, v20, 0
	v_lshlrev_b32_e32 v188, 16, v124
	v_and_b32_e32 v189, s69, v124
	ds_write_b128 v139, v[180:183] offset:8192
	v_mfma_f32_16x16x4_f32 v[16:19], v26, v22, v[16:19]
	ds_write_b128 v139, v[184:187] offset:17408
	ds_write2_b32 v140, v188, v189 offset1:4
	global_load_dwordx2 v[120:121], v130, s[8:9]
	v_mfma_f32_16x16x4_f32 v[8:11], v1, v21, v[8:11]
	global_load_dwordx2 v[122:123], v130, s[8:9] offset:1024
	global_load_dword v124, v131, s[8:9]
	s_add_u32 s8, s8, 0x34000
	s_addc_u32 s9, s9, 0
	s_waitcnt lgkmcnt(3)
	v_mfma_f32_16x16x4_f32 v[16:19], v27, v23, v[16:19]
	v_add_f32_e32 v112, v104, v105
	v_add_f32_e32 v112, v112, v106
	v_add_f32_e32 v112, v112, v107
	v_mfma_f32_16x16x4_f32 v[12:15], v5, v21, v[12:15]
	v_add_f32_e32 v112, v112, v108
	v_add_f32_e32 v112, v112, v109
	v_add_f32_e32 v112, v112, v110
	v_mfma_f32_16x16x4_f32 v[8:11], v2, v22, v[8:11]
	v_add_f32_e32 v112, v112, v111
	v_mul_f32_e32 v113, v112, v112
	v_cvt_pk_bf16_f32 v116, v112, v129
	v_mfma_f32_16x16x4_f32 v[12:15], v6, v22, v[12:15]
	v_mov_b32_e32 v117, v112
	v_mov_b32_e32 v118, v113
	global_store_short v132, v116, s[10:11]
	v_mfma_f32_16x16x4_f32 v[8:11], v3, v23, v[8:11]
	s_nop 1
	v_permlane16_swap_b32_e32 v112, v117
	v_permlane16_swap_b32_e32 v113, v118
	v_add_f32_e32 v112, v112, v117
	v_mfma_f32_16x16x4_f32 v[12:15], v7, v23, v[12:15]
	v_add_f32_e32 v113, v113, v118
	s_nop 1
	v_add_f32_dpp v112, v112, v112 row_ror:8 row_mask:0xf bank_mask:0xf
	v_add_f32_dpp v113, v113, v113 row_ror:8 row_mask:0xf bank_mask:0xf
	s_waitcnt lgkmcnt(7)
	v_mul_f32_e32 v28, v28, v44
	v_mul_f32_e32 v29, v29, v45
	v_mul_f32_e32 v30, v30, v46
	v_mul_f32_e32 v31, v31, v47
	v_pk_mul_f32 v[0:1], v[0:1], v[52:53]
	v_pk_mul_f32 v[2:3], v[2:3], v[52:53]
	v_pk_mul_f32 v[4:5], v[4:5], v[52:53]
	v_pk_mul_f32 v[6:7], v[6:7], v[52:53]
	v_pk_mul_f32 v[16:17], v[16:17], v[48:49]
	v_pk_mul_f32 v[18:19], v[18:19], v[50:51]
	s_nop 1
	v_permlane16_swap_b32_e32 v16, v17
	v_permlane16_swap_b32_e32 v18, v19
	s_nop 1
	v_permlane32_swap_b32_e32 v16, v18
	v_permlane32_swap_b32_e32 v17, v19
	s_nop 1
	v_mfma_f32_16x16x4_f32 v[8:11], v32, v16, v[8:11]
	s_nop 1
	v_add_f32_dpp v112, v112, v112 row_ror:4 row_mask:0xf bank_mask:0xf
	v_add_f32_dpp v113, v113, v113 row_ror:4 row_mask:0xf bank_mask:0xf
	s_nop 1
	v_add_f32_dpp v112, v112, v112 row_ror:2 row_mask:0xf bank_mask:0xf
	v_mfma_f32_16x16x4_f32 v[12:15], v33, v16, v[12:15]
	v_add_f32_dpp v113, v113, v113 row_ror:2 row_mask:0xf bank_mask:0xf
	s_nop 1
	v_add_f32_dpp v112, v112, v112 row_ror:1 row_mask:0xf bank_mask:0xf
	v_add_f32_dpp v113, v113, v113 row_ror:1 row_mask:0xf bank_mask:0xf
	v_mfma_f32_16x16x4_f32 v[8:11], v34, v17, v[8:11]
	v_mov_b32_e32 v114, 0
	v_mov_b32_e32 v115, 0
	s_nop 0
	s_mov_b64 exec, s[18:19]
	global_store_dwordx4 v133, v[112:115], s[12:13]
	s_mov_b64 exec, -1
	s_cmp_eq_u32 s15, 512
	s_cselect_b32 s20, 0, 0x10000
	s_cselect_b32 s21, 0, 0x1000
	s_add_u32 s10, s10, s20
	s_addc_u32 s11, s11, 0
	s_add_u32 s12, s12, s21
	s_addc_u32 s13, s13, 0
	v_mfma_f32_16x16x4_f32 v[12:15], v35, v17, v[12:15]
	v_mfma_f32_16x16x4_f32 v[8:11], v36, v18, v[8:11]
	v_mfma_f32_16x16x4_f32 v[12:15], v37, v18, v[12:15]
	v_mfma_f32_16x16x4_f32 v[8:11], v38, v19, v[8:11]
	v_mfma_f32_16x16x4_f32 v[12:15], v39, v19, v[12:15]
	v_mfma_f32_16x16x4_f32 v[0:3], v28, v32, v[0:3]
	v_mfma_f32_16x16x4_f32 v[4:7], v28, v33, v[4:7]
	v_mfma_f32_16x16x4_f32 v[0:3], v29, v34, v[0:3]
	v_mfma_f32_16x16x4_f32 v[4:7], v29, v35, v[4:7]
	v_mfma_f32_16x16x4_f32 v[0:3], v30, v36, v[0:3]
	v_mfma_f32_16x16x4_f32 v[4:7], v30, v37, v[4:7]
	v_mfma_f32_16x16x4_f32 v[0:3], v31, v38, v[0:3]
	v_mfma_f32_16x16x4_f32 v[4:7], v31, v39, v[4:7]
	s_nop 1
	ds_write_b128 v60, v[8:11]
	ds_write_b128 v60, v[12:15] offset:64
	s_sub_u32 s15, s15, 1
	s_waitcnt lgkmcnt(0)
	s_barrier
	s_cmp_lg_u32 s15, 0
	s_cbranch_scc1 .Lgla_loop_ret
